# 9920 of the 11008 layer-1 FFN gate-weight conversion tiles moved from the HGRN2 phase into the idle tail of the half-GLU GEMM phase (hand-written pipelined transposing converter on the 248 workgroups
# baseline (speedup 1.0000x reference)
.Ldc_go:
	s_add_i32 s6, s6, 0x440
	s_cmp_gt_u32 s6, 0x2aff
	s_cbranch_scc1 .Ldc_done
	s_load_dwordx2 s[20:21], s[0:1], 0xf8
	v_mbcnt_lo_u32_b32 v1, -1, 0
	v_mbcnt_hi_u32_b32 v1, -1, v1
	v_lshrrev_b32_e32 v2, 4, v1
	v_and_b32_e32 v3, 15, v1
	v_mul_u32_u24_e32 v200, 0xac000, v2
	v_lshl_add_u32 v200, v3, 4, v200
	s_lshl_b32 s8, s3, 14
	v_mul_u32_u24_e32 v201, 0x220, v3
	v_lshl_add_u32 v201, v2, 5, v201
	v_add_u32_e32 v201, s8, v201
	v_lshrrev_b32_e32 v2, 3, v1
	v_and_b32_e32 v3, 7, v1
	v_mul_u32_u24_e32 v202, 0x88, v2
	v_lshl_add_u32 v202, v3, 4, v202
	v_add_u32_e32 v202, s8, v202
	v_lshlrev_b32_e32 v203, 13, v2
	v_lshl_add_u32 v203, v3, 4, v203
	s_add_u32 s22, s38, 0x21600000
	s_addc_u32 s23, s39, 0
	s_waitcnt lgkmcnt(0)
	s_add_u32 s20, s20, 0xac00000
	s_addc_u32 s21, s21, 0
	s_mul_hi_u32 s8, s6, 0x5f418
	s_mul_i32 s8, s8, 0x2b00
	s_sub_i32 s25, s6, s8
	s_cmpk_gt_u32 s25, 0x2aff
	s_cselect_b32 s8, 0x2b00, 0
	s_sub_i32 s25, s25, s8
	s_and_b32 s10, s25, 63
	s_lshr_b32 s11, s25, 6
	s_mul_i32 s8, s10, 0x2b0000
	s_lshl_b32 s9, s11, 8
	s_add_i32 s8, s8, s9
	s_add_u32 s14, s20, s8
	s_addc_u32 s15, s21, 0
	global_load_dwordx4 v[2:5], v200, s[14:15] nt
	s_add_u32 s14, s14, 0xac00
	s_addc_u32 s15, s15, 0
	global_load_dwordx4 v[6:9], v200, s[14:15] nt
	s_add_u32 s14, s14, 0xac00
	s_addc_u32 s15, s15, 0
	global_load_dwordx4 v[10:13], v200, s[14:15] nt
	s_add_u32 s14, s14, 0xac00
	s_addc_u32 s15, s15, 0
	global_load_dwordx4 v[14:17], v200, s[14:15] nt
	s_add_u32 s14, s14, 0xac00
	s_addc_u32 s15, s15, 0
	global_load_dwordx4 v[18:21], v200, s[14:15] nt
	s_add_u32 s14, s14, 0xac00
	s_addc_u32 s15, s15, 0
	global_load_dwordx4 v[22:25], v200, s[14:15] nt
	s_add_u32 s14, s14, 0xac00
	s_addc_u32 s15, s15, 0
	global_load_dwordx4 v[26:29], v200, s[14:15] nt
	s_add_u32 s14, s14, 0xac00
	s_addc_u32 s15, s15, 0
	global_load_dwordx4 v[30:33], v200, s[14:15] nt
	s_add_u32 s14, s14, 0xac00
	s_addc_u32 s15, s15, 0
	global_load_dwordx4 v[34:37], v200, s[14:15] nt
	s_add_u32 s14, s14, 0xac00
	s_addc_u32 s15, s15, 0
	global_load_dwordx4 v[38:41], v200, s[14:15] nt
	s_add_u32 s14, s14, 0xac00
	s_addc_u32 s15, s15, 0
	global_load_dwordx4 v[42:45], v200, s[14:15] nt
	s_add_u32 s14, s14, 0xac00
	s_addc_u32 s15, s15, 0
	global_load_dwordx4 v[46:49], v200, s[14:15] nt
	s_add_u32 s14, s14, 0xac00
	s_addc_u32 s15, s15, 0
	global_load_dwordx4 v[50:53], v200, s[14:15] nt
	s_add_u32 s14, s14, 0xac00
	s_addc_u32 s15, s15, 0
	global_load_dwordx4 v[54:57], v200, s[14:15] nt
	s_add_u32 s14, s14, 0xac00
	s_addc_u32 s15, s15, 0
	global_load_dwordx4 v[58:61], v200, s[14:15] nt
	s_add_u32 s14, s14, 0xac00
	s_addc_u32 s15, s15, 0
	global_load_dwordx4 v[62:65], v200, s[14:15] nt
.Ldc_loop:
	s_add_i32 s24, s6, s7
	s_cmp_gt_u32 s24, 0x2aff
	s_cbranch_scc1 .Ldc_lastA
	s_mul_hi_u32 s8, s24, 0x5f418
	s_mul_i32 s8, s8, 0x2b00
	s_sub_i32 s25, s24, s8
	s_cmpk_gt_u32 s25, 0x2aff
	s_cselect_b32 s8, 0x2b00, 0
	s_sub_i32 s25, s25, s8
	s_and_b32 s10, s25, 63
	s_lshr_b32 s11, s25, 6
	s_mul_i32 s8, s10, 0x2b0000
	s_lshl_b32 s9, s11, 8
	s_add_i32 s8, s8, s9
	s_add_u32 s14, s20, s8
	s_addc_u32 s15, s21, 0
	global_load_dwordx4 v[66:69], v200, s[14:15] nt
	s_add_u32 s14, s14, 0xac00
	s_addc_u32 s15, s15, 0
	global_load_dwordx4 v[70:73], v200, s[14:15] nt
	s_add_u32 s14, s14, 0xac00
	s_addc_u32 s15, s15, 0
	global_load_dwordx4 v[74:77], v200, s[14:15] nt
	s_add_u32 s14, s14, 0xac00
	s_addc_u32 s15, s15, 0
	global_load_dwordx4 v[78:81], v200, s[14:15] nt
	s_add_u32 s14, s14, 0xac00
	s_addc_u32 s15, s15, 0
	global_load_dwordx4 v[82:85], v200, s[14:15] nt
	s_add_u32 s14, s14, 0xac00
	s_addc_u32 s15, s15, 0
	global_load_dwordx4 v[86:89], v200, s[14:15] nt
	s_add_u32 s14, s14, 0xac00
	s_addc_u32 s15, s15, 0
	global_load_dwordx4 v[90:93], v200, s[14:15] nt
	s_add_u32 s14, s14, 0xac00
	s_addc_u32 s15, s15, 0
	global_load_dwordx4 v[94:97], v200, s[14:15] nt
	s_add_u32 s14, s14, 0xac00
	s_addc_u32 s15, s15, 0
	global_load_dwordx4 v[98:101], v200, s[14:15] nt
	s_add_u32 s14, s14, 0xac00
	s_addc_u32 s15, s15, 0
	global_load_dwordx4 v[102:105], v200, s[14:15] nt
	s_add_u32 s14, s14, 0xac00
	s_addc_u32 s15, s15, 0
	global_load_dwordx4 v[106:109], v200, s[14:15] nt
	s_add_u32 s14, s14, 0xac00
	s_addc_u32 s15, s15, 0
	global_load_dwordx4 v[110:113], v200, s[14:15] nt
	s_add_u32 s14, s14, 0xac00
	s_addc_u32 s15, s15, 0
	global_load_dwordx4 v[114:117], v200, s[14:15] nt
	s_add_u32 s14, s14, 0xac00
	s_addc_u32 s15, s15, 0
	global_load_dwordx4 v[118:121], v200, s[14:15] nt
	s_add_u32 s14, s14, 0xac00
	s_addc_u32 s15, s15, 0
	global_load_dwordx4 v[122:125], v200, s[14:15] nt
	s_add_u32 s14, s14, 0xac00
	s_addc_u32 s15, s15, 0
	global_load_dwordx4 v[126:129], v200, s[14:15] nt
	s_waitcnt vmcnt(16)
	s_mul_hi_u32 s8, s6, 0x5f418
	s_mul_i32 s8, s8, 0x2b00
	s_sub_i32 s25, s6, s8
	s_cmpk_gt_u32 s25, 0x2aff
	s_cselect_b32 s8, 0x2b00, 0
	s_sub_i32 s25, s25, s8
	s_and_b32 s10, s25, 63
	s_lshr_b32 s11, s25, 6
	s_lshr_b32 s8, s11, 1
	s_lshl_b32 s8, s8, 8
	s_and_b32 s9, s11, 1
	s_lshl_b32 s9, s9, 6
	s_add_i32 s8, s8, s9
	s_lshl_b32 s8, s8, 13
	s_lshl_b32 s9, s10, 7
	s_add_i32 s8, s8, s9
	s_add_u32 s18, s22, s8
	s_addc_u32 s19, s23, 0
	v_cvt_pk_bf16_f32 v130, v2, v6
	v_cvt_pk_bf16_f32 v131, v10, v14
	v_cvt_pk_bf16_f32 v132, v18, v22
	v_cvt_pk_bf16_f32 v133, v26, v30
	v_cvt_pk_bf16_f32 v134, v34, v38
	v_cvt_pk_bf16_f32 v135, v42, v46
	v_cvt_pk_bf16_f32 v136, v50, v54
	v_cvt_pk_bf16_f32 v137, v58, v62
	v_cvt_pk_bf16_f32 v138, v3, v7
	v_cvt_pk_bf16_f32 v139, v11, v15
	v_cvt_pk_bf16_f32 v140, v19, v23
	v_cvt_pk_bf16_f32 v141, v27, v31
	v_cvt_pk_bf16_f32 v142, v35, v39
	v_cvt_pk_bf16_f32 v143, v43, v47
	v_cvt_pk_bf16_f32 v144, v51, v55
	v_cvt_pk_bf16_f32 v145, v59, v63
	v_cvt_pk_bf16_f32 v146, v4, v8
	v_cvt_pk_bf16_f32 v147, v12, v16
	v_cvt_pk_bf16_f32 v148, v20, v24
	v_cvt_pk_bf16_f32 v149, v28, v32
	v_cvt_pk_bf16_f32 v150, v36, v40
	v_cvt_pk_bf16_f32 v151, v44, v48
	v_cvt_pk_bf16_f32 v152, v52, v56
	v_cvt_pk_bf16_f32 v153, v60, v64
	v_cvt_pk_bf16_f32 v154, v5, v9
	v_cvt_pk_bf16_f32 v155, v13, v17
	v_cvt_pk_bf16_f32 v156, v21, v25
	v_cvt_pk_bf16_f32 v157, v29, v33
	v_cvt_pk_bf16_f32 v158, v37, v41
	v_cvt_pk_bf16_f32 v159, v45, v49
	v_cvt_pk_bf16_f32 v160, v53, v57
	v_cvt_pk_bf16_f32 v161, v61, v65
	ds_write_b64 v201, v[130:131]
	ds_write_b64 v201, v[132:133] offset:8
	ds_write_b64 v201, v[134:135] offset:16
	ds_write_b64 v201, v[136:137] offset:24
	ds_write_b64 v201, v[138:139] offset:136
	ds_write_b64 v201, v[140:141] offset:144
	ds_write_b64 v201, v[142:143] offset:152
	ds_write_b64 v201, v[144:145] offset:160
	ds_write_b64 v201, v[146:147] offset:272
	ds_write_b64 v201, v[148:149] offset:280
	ds_write_b64 v201, v[150:151] offset:288
	ds_write_b64 v201, v[152:153] offset:296
	ds_write_b64 v201, v[154:155] offset:408
	ds_write_b64 v201, v[156:157] offset:416
	ds_write_b64 v201, v[158:159] offset:424
	ds_write_b64 v201, v[160:161] offset:432
	s_waitcnt lgkmcnt(0)
	ds_read_b64 v[162:163], v202
	ds_read_b64 v[164:165], v202 offset:8
	ds_read_b64 v[166:167], v202 offset:1088
	ds_read_b64 v[168:169], v202 offset:1096
	ds_read_b64 v[170:171], v202 offset:2176
	ds_read_b64 v[172:173], v202 offset:2184
	ds_read_b64 v[174:175], v202 offset:3264
	ds_read_b64 v[176:177], v202 offset:3272
	ds_read_b64 v[178:179], v202 offset:4352
	ds_read_b64 v[180:181], v202 offset:4360
	ds_read_b64 v[182:183], v202 offset:5440
	ds_read_b64 v[184:185], v202 offset:5448
	ds_read_b64 v[186:187], v202 offset:6528
	ds_read_b64 v[188:189], v202 offset:6536
	ds_read_b64 v[190:191], v202 offset:7616
	ds_read_b64 v[192:193], v202 offset:7624
	s_waitcnt lgkmcnt(14)
	global_store_dwordx4 v203, v[162:165], s[18:19]
	s_add_u32 s18, s18, 0x10000
	s_addc_u32 s19, s19, 0
	s_waitcnt lgkmcnt(12)
	global_store_dwordx4 v203, v[166:169], s[18:19]
	s_add_u32 s18, s18, 0x10000
	s_addc_u32 s19, s19, 0
	s_waitcnt lgkmcnt(10)
	global_store_dwordx4 v203, v[170:173], s[18:19]
	s_add_u32 s18, s18, 0x10000
	s_addc_u32 s19, s19, 0
	s_waitcnt lgkmcnt(8)
	global_store_dwordx4 v203, v[174:177], s[18:19]
	s_add_u32 s18, s18, 0x10000
	s_addc_u32 s19, s19, 0
	s_waitcnt lgkmcnt(6)
	global_store_dwordx4 v203, v[178:181], s[18:19]
	s_add_u32 s18, s18, 0x10000
	s_addc_u32 s19, s19, 0
	s_waitcnt lgkmcnt(4)
	global_store_dwordx4 v203, v[182:185], s[18:19]
	s_add_u32 s18, s18, 0x10000
	s_addc_u32 s19, s19, 0
	s_waitcnt lgkmcnt(2)
	global_store_dwordx4 v203, v[186:189], s[18:19]
	s_add_u32 s18, s18, 0x10000
	s_addc_u32 s19, s19, 0
	s_waitcnt lgkmcnt(0)
	global_store_dwordx4 v203, v[190:193], s[18:19]
	s_mov_b32 s6, s24
	s_add_i32 s24, s6, s7
	s_cmp_gt_u32 s24, 0x2aff
	s_cbranch_scc1 .Ldc_lastB
	s_mul_hi_u32 s8, s24, 0x5f418
	s_mul_i32 s8, s8, 0x2b00
	s_sub_i32 s25, s24, s8
	s_cmpk_gt_u32 s25, 0x2aff
	s_cselect_b32 s8, 0x2b00, 0
	s_sub_i32 s25, s25, s8
	s_and_b32 s10, s25, 63
	s_lshr_b32 s11, s25, 6
	s_mul_i32 s8, s10, 0x2b0000
	s_lshl_b32 s9, s11, 8
	s_add_i32 s8, s8, s9
	s_add_u32 s14, s20, s8
	s_addc_u32 s15, s21, 0
	global_load_dwordx4 v[2:5], v200, s[14:15] nt
	s_add_u32 s14, s14, 0xac00
	s_addc_u32 s15, s15, 0
	global_load_dwordx4 v[6:9], v200, s[14:15] nt
	s_add_u32 s14, s14, 0xac00
	s_addc_u32 s15, s15, 0
	global_load_dwordx4 v[10:13], v200, s[14:15] nt
	s_add_u32 s14, s14, 0xac00
	s_addc_u32 s15, s15, 0
	global_load_dwordx4 v[14:17], v200, s[14:15] nt
	s_add_u32 s14, s14, 0xac00
	s_addc_u32 s15, s15, 0
	global_load_dwordx4 v[18:21], v200, s[14:15] nt
	s_add_u32 s14, s14, 0xac00
	s_addc_u32 s15, s15, 0
	global_load_dwordx4 v[22:25], v200, s[14:15] nt
	s_add_u32 s14, s14, 0xac00
	s_addc_u32 s15, s15, 0
	global_load_dwordx4 v[26:29], v200, s[14:15] nt
	s_add_u32 s14, s14, 0xac00
	s_addc_u32 s15, s15, 0
	global_load_dwordx4 v[30:33], v200, s[14:15] nt
	s_add_u32 s14, s14, 0xac00
	s_addc_u32 s15, s15, 0
	global_load_dwordx4 v[34:37], v200, s[14:15] nt
	s_add_u32 s14, s14, 0xac00
	s_addc_u32 s15, s15, 0
	global_load_dwordx4 v[38:41], v200, s[14:15] nt
	s_add_u32 s14, s14, 0xac00
	s_addc_u32 s15, s15, 0
	global_load_dwordx4 v[42:45], v200, s[14:15] nt
	s_add_u32 s14, s14, 0xac00
	s_addc_u32 s15, s15, 0
	global_load_dwordx4 v[46:49], v200, s[14:15] nt
	s_add_u32 s14, s14, 0xac00
	s_addc_u32 s15, s15, 0
	global_load_dwordx4 v[50:53], v200, s[14:15] nt
	s_add_u32 s14, s14, 0xac00
	s_addc_u32 s15, s15, 0
	global_load_dwordx4 v[54:57], v200, s[14:15] nt
	s_add_u32 s14, s14, 0xac00
	s_addc_u32 s15, s15, 0
	global_load_dwordx4 v[58:61], v200, s[14:15] nt
	s_add_u32 s14, s14, 0xac00
	s_addc_u32 s15, s15, 0
	global_load_dwordx4 v[62:65], v200, s[14:15] nt
	s_waitcnt vmcnt(16)
	s_mul_hi_u32 s8, s6, 0x5f418
	s_mul_i32 s8, s8, 0x2b00
	s_sub_i32 s25, s6, s8
	s_cmpk_gt_u32 s25, 0x2aff
	s_cselect_b32 s8, 0x2b00, 0
	s_sub_i32 s25, s25, s8
	s_and_b32 s10, s25, 63
	s_lshr_b32 s11, s25, 6
	s_lshr_b32 s8, s11, 1
	s_lshl_b32 s8, s8, 8
	s_and_b32 s9, s11, 1
	s_lshl_b32 s9, s9, 6
	s_add_i32 s8, s8, s9
	s_lshl_b32 s8, s8, 13
	s_lshl_b32 s9, s10, 7
	s_add_i32 s8, s8, s9
	s_add_u32 s18, s22, s8
	s_addc_u32 s19, s23, 0
	v_cvt_pk_bf16_f32 v130, v66, v70
	v_cvt_pk_bf16_f32 v131, v74, v78
	v_cvt_pk_bf16_f32 v132, v82, v86
	v_cvt_pk_bf16_f32 v133, v90, v94
	v_cvt_pk_bf16_f32 v134, v98, v102
	v_cvt_pk_bf16_f32 v135, v106, v110
	v_cvt_pk_bf16_f32 v136, v114, v118
	v_cvt_pk_bf16_f32 v137, v122, v126
	v_cvt_pk_bf16_f32 v138, v67, v71
	v_cvt_pk_bf16_f32 v139, v75, v79
	v_cvt_pk_bf16_f32 v140, v83, v87
	v_cvt_pk_bf16_f32 v141, v91, v95
	v_cvt_pk_bf16_f32 v142, v99, v103
	v_cvt_pk_bf16_f32 v143, v107, v111
	v_cvt_pk_bf16_f32 v144, v115, v119
	v_cvt_pk_bf16_f32 v145, v123, v127
	v_cvt_pk_bf16_f32 v146, v68, v72
	v_cvt_pk_bf16_f32 v147, v76, v80
	v_cvt_pk_bf16_f32 v148, v84, v88
	v_cvt_pk_bf16_f32 v149, v92, v96
	v_cvt_pk_bf16_f32 v150, v100, v104
	v_cvt_pk_bf16_f32 v151, v108, v112
	v_cvt_pk_bf16_f32 v152, v116, v120
	v_cvt_pk_bf16_f32 v153, v124, v128
	v_cvt_pk_bf16_f32 v154, v69, v73
	v_cvt_pk_bf16_f32 v155, v77, v81
	v_cvt_pk_bf16_f32 v156, v85, v89
	v_cvt_pk_bf16_f32 v157, v93, v97
	v_cvt_pk_bf16_f32 v158, v101, v105
	v_cvt_pk_bf16_f32 v159, v109, v113
	v_cvt_pk_bf16_f32 v160, v117, v121
	v_cvt_pk_bf16_f32 v161, v125, v129
	ds_write_b64 v201, v[130:131]
	ds_write_b64 v201, v[132:133] offset:8
	ds_write_b64 v201, v[134:135] offset:16
	ds_write_b64 v201, v[136:137] offset:24
	ds_write_b64 v201, v[138:139] offset:136
	ds_write_b64 v201, v[140:141] offset:144
	ds_write_b64 v201, v[142:143] offset:152
	ds_write_b64 v201, v[144:145] offset:160
	ds_write_b64 v201, v[146:147] offset:272
	ds_write_b64 v201, v[148:149] offset:280
	ds_write_b64 v201, v[150:151] offset:288
	ds_write_b64 v201, v[152:153] offset:296
	ds_write_b64 v201, v[154:155] offset:408
	ds_write_b64 v201, v[156:157] offset:416
	ds_write_b64 v201, v[158:159] offset:424
	ds_write_b64 v201, v[160:161] offset:432
	s_waitcnt lgkmcnt(0)
	ds_read_b64 v[162:163], v202
	ds_read_b64 v[164:165], v202 offset:8
	ds_read_b64 v[166:167], v202 offset:1088
	ds_read_b64 v[168:169], v202 offset:1096
	ds_read_b64 v[170:171], v202 offset:2176
	ds_read_b64 v[172:173], v202 offset:2184
	ds_read_b64 v[174:175], v202 offset:3264
	ds_read_b64 v[176:177], v202 offset:3272
	ds_read_b64 v[178:179], v202 offset:4352
	ds_read_b64 v[180:181], v202 offset:4360
	ds_read_b64 v[182:183], v202 offset:5440
	ds_read_b64 v[184:185], v202 offset:5448
	ds_read_b64 v[186:187], v202 offset:6528
	ds_read_b64 v[188:189], v202 offset:6536
	ds_read_b64 v[190:191], v202 offset:7616
	ds_read_b64 v[192:193], v202 offset:7624
	s_waitcnt lgkmcnt(14)
	global_store_dwordx4 v203, v[162:165], s[18:19]
	s_add_u32 s18, s18, 0x10000
	s_addc_u32 s19, s19, 0
	s_waitcnt lgkmcnt(12)
	global_store_dwordx4 v203, v[166:169], s[18:19]
	s_add_u32 s18, s18, 0x10000
	s_addc_u32 s19, s19, 0
	s_waitcnt lgkmcnt(10)
	global_store_dwordx4 v203, v[170:173], s[18:19]
	s_add_u32 s18, s18, 0x10000
	s_addc_u32 s19, s19, 0
	s_waitcnt lgkmcnt(8)
	global_store_dwordx4 v203, v[174:177], s[18:19]
	s_add_u32 s18, s18, 0x10000
	s_addc_u32 s19, s19, 0
	s_waitcnt lgkmcnt(6)
	global_store_dwordx4 v203, v[178:181], s[18:19]
	s_add_u32 s18, s18, 0x10000
	s_addc_u32 s19, s19, 0
	s_waitcnt lgkmcnt(4)
	global_store_dwordx4 v203, v[182:185], s[18:19]
	s_add_u32 s18, s18, 0x10000
	s_addc_u32 s19, s19, 0
	s_waitcnt lgkmcnt(2)
	global_store_dwordx4 v203, v[186:189], s[18:19]
	s_add_u32 s18, s18, 0x10000
	s_addc_u32 s19, s19, 0
	s_waitcnt lgkmcnt(0)
	global_store_dwordx4 v203, v[190:193], s[18:19]
	s_mov_b32 s6, s24
	s_branch .Ldc_loop
.Ldc_lastA:
	s_waitcnt vmcnt(0)
	s_mul_hi_u32 s8, s6, 0x5f418
	s_mul_i32 s8, s8, 0x2b00
	s_sub_i32 s25, s6, s8
	s_cmpk_gt_u32 s25, 0x2aff
	s_cselect_b32 s8, 0x2b00, 0
	s_sub_i32 s25, s25, s8
	s_and_b32 s10, s25, 63
	s_lshr_b32 s11, s25, 6
	s_lshr_b32 s8, s11, 1
	s_lshl_b32 s8, s8, 8
	s_and_b32 s9, s11, 1
	s_lshl_b32 s9, s9, 6
	s_add_i32 s8, s8, s9
	s_lshl_b32 s8, s8, 13
	s_lshl_b32 s9, s10, 7
	s_add_i32 s8, s8, s9
	s_add_u32 s18, s22, s8
	s_addc_u32 s19, s23, 0
	v_cvt_pk_bf16_f32 v130, v2, v6
	v_cvt_pk_bf16_f32 v131, v10, v14
	v_cvt_pk_bf16_f32 v132, v18, v22
	v_cvt_pk_bf16_f32 v133, v26, v30
	v_cvt_pk_bf16_f32 v134, v34, v38
	v_cvt_pk_bf16_f32 v135, v42, v46
	v_cvt_pk_bf16_f32 v136, v50, v54
	v_cvt_pk_bf16_f32 v137, v58, v62
	v_cvt_pk_bf16_f32 v138, v3, v7
	v_cvt_pk_bf16_f32 v139, v11, v15
	v_cvt_pk_bf16_f32 v140, v19, v23
	v_cvt_pk_bf16_f32 v141, v27, v31
	v_cvt_pk_bf16_f32 v142, v35, v39
	v_cvt_pk_bf16_f32 v143, v43, v47
	v_cvt_pk_bf16_f32 v144, v51, v55
	v_cvt_pk_bf16_f32 v145, v59, v63
	v_cvt_pk_bf16_f32 v146, v4, v8
	v_cvt_pk_bf16_f32 v147, v12, v16
	v_cvt_pk_bf16_f32 v148, v20, v24
	v_cvt_pk_bf16_f32 v149, v28, v32
	v_cvt_pk_bf16_f32 v150, v36, v40
	v_cvt_pk_bf16_f32 v151, v44, v48
	v_cvt_pk_bf16_f32 v152, v52, v56
	v_cvt_pk_bf16_f32 v153, v60, v64
	v_cvt_pk_bf16_f32 v154, v5, v9
	v_cvt_pk_bf16_f32 v155, v13, v17
	v_cvt_pk_bf16_f32 v156, v21, v25
	v_cvt_pk_bf16_f32 v157, v29, v33
	v_cvt_pk_bf16_f32 v158, v37, v41
	v_cvt_pk_bf16_f32 v159, v45, v49
	v_cvt_pk_bf16_f32 v160, v53, v57
	v_cvt_pk_bf16_f32 v161, v61, v65
	ds_write_b64 v201, v[130:131]
	ds_write_b64 v201, v[132:133] offset:8
	ds_write_b64 v201, v[134:135] offset:16
	ds_write_b64 v201, v[136:137] offset:24
	ds_write_b64 v201, v[138:139] offset:136
	ds_write_b64 v201, v[140:141] offset:144
	ds_write_b64 v201, v[142:143] offset:152
	ds_write_b64 v201, v[144:145] offset:160
	ds_write_b64 v201, v[146:147] offset:272
	ds_write_b64 v201, v[148:149] offset:280
	ds_write_b64 v201, v[150:151] offset:288
	ds_write_b64 v201, v[152:153] offset:296
	ds_write_b64 v201, v[154:155] offset:408
	ds_write_b64 v201, v[156:157] offset:416
	ds_write_b64 v201, v[158:159] offset:424
	ds_write_b64 v201, v[160:161] offset:432
	s_waitcnt lgkmcnt(0)
	ds_read_b64 v[162:163], v202
	ds_read_b64 v[164:165], v202 offset:8
	ds_read_b64 v[166:167], v202 offset:1088
	ds_read_b64 v[168:169], v202 offset:1096
	ds_read_b64 v[170:171], v202 offset:2176
	ds_read_b64 v[172:173], v202 offset:2184
	ds_read_b64 v[174:175], v202 offset:3264
	ds_read_b64 v[176:177], v202 offset:3272
	ds_read_b64 v[178:179], v202 offset:4352
	ds_read_b64 v[180:181], v202 offset:4360
	ds_read_b64 v[182:183], v202 offset:5440
	ds_read_b64 v[184:185], v202 offset:5448
	ds_read_b64 v[186:187], v202 offset:6528
	ds_read_b64 v[188:189], v202 offset:6536
	ds_read_b64 v[190:191], v202 offset:7616
	ds_read_b64 v[192:193], v202 offset:7624
	s_waitcnt lgkmcnt(14)
	global_store_dwordx4 v203, v[162:165], s[18:19]
	s_add_u32 s18, s18, 0x10000
	s_addc_u32 s19, s19, 0
	s_waitcnt lgkmcnt(12)
	global_store_dwordx4 v203, v[166:169], s[18:19]
	s_add_u32 s18, s18, 0x10000
	s_addc_u32 s19, s19, 0
	s_waitcnt lgkmcnt(10)
	global_store_dwordx4 v203, v[170:173], s[18:19]
	s_add_u32 s18, s18, 0x10000
	s_addc_u32 s19, s19, 0
	s_waitcnt lgkmcnt(8)
	global_store_dwordx4 v203, v[174:177], s[18:19]
	s_add_u32 s18, s18, 0x10000
	s_addc_u32 s19, s19, 0
	s_waitcnt lgkmcnt(6)
	global_store_dwordx4 v203, v[178:181], s[18:19]
	s_add_u32 s18, s18, 0x10000
	s_addc_u32 s19, s19, 0
	s_waitcnt lgkmcnt(4)
	global_store_dwordx4 v203, v[182:185], s[18:19]
	s_add_u32 s18, s18, 0x10000
	s_addc_u32 s19, s19, 0
	s_waitcnt lgkmcnt(2)
	global_store_dwordx4 v203, v[186:189], s[18:19]
	s_add_u32 s18, s18, 0x10000
	s_addc_u32 s19, s19, 0
	s_waitcnt lgkmcnt(0)
	global_store_dwordx4 v203, v[190:193], s[18:19]
	s_branch .Ldc_done
.Ldc_lastB:
	s_waitcnt vmcnt(0)
	s_mul_hi_u32 s8, s6, 0x5f418
	s_mul_i32 s8, s8, 0x2b00
	s_sub_i32 s25, s6, s8
	s_cmpk_gt_u32 s25, 0x2aff
	s_cselect_b32 s8, 0x2b00, 0
	s_sub_i32 s25, s25, s8
	s_and_b32 s10, s25, 63
	s_lshr_b32 s11, s25, 6
	s_lshr_b32 s8, s11, 1
	s_lshl_b32 s8, s8, 8
	s_and_b32 s9, s11, 1
	s_lshl_b32 s9, s9, 6
	s_add_i32 s8, s8, s9
	s_lshl_b32 s8, s8, 13
	s_lshl_b32 s9, s10, 7
	s_add_i32 s8, s8, s9
	s_add_u32 s18, s22, s8
	s_addc_u32 s19, s23, 0
	v_cvt_pk_bf16_f32 v130, v66, v70
	v_cvt_pk_bf16_f32 v131, v74, v78
	v_cvt_pk_bf16_f32 v132, v82, v86
	v_cvt_pk_bf16_f32 v133, v90, v94
	v_cvt_pk_bf16_f32 v134, v98, v102
	v_cvt_pk_bf16_f32 v135, v106, v110
	v_cvt_pk_bf16_f32 v136, v114, v118
	v_cvt_pk_bf16_f32 v137, v122, v126
	v_cvt_pk_bf16_f32 v138, v67, v71
	v_cvt_pk_bf16_f32 v139, v75, v79
	v_cvt_pk_bf16_f32 v140, v83, v87
	v_cvt_pk_bf16_f32 v141, v91, v95
	v_cvt_pk_bf16_f32 v142, v99, v103
	v_cvt_pk_bf16_f32 v143, v107, v111
	v_cvt_pk_bf16_f32 v144, v115, v119
	v_cvt_pk_bf16_f32 v145, v123, v127
	v_cvt_pk_bf16_f32 v146, v68, v72
	v_cvt_pk_bf16_f32 v147, v76, v80
	v_cvt_pk_bf16_f32 v148, v84, v88
	v_cvt_pk_bf16_f32 v149, v92, v96
	v_cvt_pk_bf16_f32 v150, v100, v104
	v_cvt_pk_bf16_f32 v151, v108, v112
	v_cvt_pk_bf16_f32 v152, v116, v120
	v_cvt_pk_bf16_f32 v153, v124, v128
	v_cvt_pk_bf16_f32 v154, v69, v73
	v_cvt_pk_bf16_f32 v155, v77, v81
	v_cvt_pk_bf16_f32 v156, v85, v89
	v_cvt_pk_bf16_f32 v157, v93, v97
	v_cvt_pk_bf16_f32 v158, v101, v105
	v_cvt_pk_bf16_f32 v159, v109, v113
	v_cvt_pk_bf16_f32 v160, v117, v121
	v_cvt_pk_bf16_f32 v161, v125, v129
	ds_write_b64 v201, v[130:131]
	ds_write_b64 v201, v[132:133] offset:8
	ds_write_b64 v201, v[134:135] offset:16
	ds_write_b64 v201, v[136:137] offset:24
	ds_write_b64 v201, v[138:139] offset:136
	ds_write_b64 v201, v[140:141] offset:144
	ds_write_b64 v201, v[142:143] offset:152
	ds_write_b64 v201, v[144:145] offset:160
	ds_write_b64 v201, v[146:147] offset:272
	ds_write_b64 v201, v[148:149] offset:280
	ds_write_b64 v201, v[150:151] offset:288
	ds_write_b64 v201, v[152:153] offset:296
	ds_write_b64 v201, v[154:155] offset:408
	ds_write_b64 v201, v[156:157] offset:416
	ds_write_b64 v201, v[158:159] offset:424
	ds_write_b64 v201, v[160:161] offset:432
	s_waitcnt lgkmcnt(0)
	ds_read_b64 v[162:163], v202
	ds_read_b64 v[164:165], v202 offset:8
	ds_read_b64 v[166:167], v202 offset:1088
	ds_read_b64 v[168:169], v202 offset:1096
	ds_read_b64 v[170:171], v202 offset:2176
	ds_read_b64 v[172:173], v202 offset:2184
	ds_read_b64 v[174:175], v202 offset:3264
	ds_read_b64 v[176:177], v202 offset:3272
	ds_read_b64 v[178:179], v202 offset:4352
	ds_read_b64 v[180:181], v202 offset:4360
	ds_read_b64 v[182:183], v202 offset:5440
	ds_read_b64 v[184:185], v202 offset:5448
	ds_read_b64 v[186:187], v202 offset:6528
	ds_read_b64 v[188:189], v202 offset:6536
	ds_read_b64 v[190:191], v202 offset:7616
	ds_read_b64 v[192:193], v202 offset:7624
	s_waitcnt lgkmcnt(14)
	global_store_dwordx4 v203, v[162:165], s[18:19]
	s_add_u32 s18, s18, 0x10000
	s_addc_u32 s19, s19, 0
	s_waitcnt lgkmcnt(12)
	global_store_dwordx4 v203, v[166:169], s[18:19]
	s_add_u32 s18, s18, 0x10000
	s_addc_u32 s19, s19, 0
	s_waitcnt lgkmcnt(10)
	global_store_dwordx4 v203, v[170:173], s[18:19]
	s_add_u32 s18, s18, 0x10000
	s_addc_u32 s19, s19, 0
	s_waitcnt lgkmcnt(8)
	global_store_dwordx4 v203, v[174:177], s[18:19]
	s_add_u32 s18, s18, 0x10000
	s_addc_u32 s19, s19, 0
	s_waitcnt lgkmcnt(6)
	global_store_dwordx4 v203, v[178:181], s[18:19]
	s_add_u32 s18, s18, 0x10000
	s_addc_u32 s19, s19, 0
	s_waitcnt lgkmcnt(4)
	global_store_dwordx4 v203, v[182:185], s[18:19]
	s_add_u32 s18, s18, 0x10000
	s_addc_u32 s19, s19, 0
	s_waitcnt lgkmcnt(2)
	global_store_dwordx4 v203, v[186:189], s[18:19]
	s_add_u32 s18, s18, 0x10000
	s_addc_u32 s19, s19, 0
	s_waitcnt lgkmcnt(0)
	global_store_dwordx4 v203, v[190:193], s[18:19]

.LBB0_3563:
	s_mul_hi_i32 s6, s29, 0x2fa0be83
	s_mov_b64 s[4:5], s[0:1]
	s_lshr_b32 s7, s6, 31
	s_ashr_i32 s6, s6, 5
	s_add_i32 s6, s6, s7
	s_load_dwordx2 s[30:31], s[4:5], 0x108
	s_mul_i32 s4, s6, 0xffffd500
	s_add_i32 s4, s28, s4
	v_add_u32_e32 v22, s4, v89
	v_ashrrev_i32_e32 v23, 31, v22
	s_lshl_b32 s6, s6, 6
	v_lshlrev_b64 v[22:23], 14, v[22:23]
	s_ashr_i32 s7, s6, 31
	s_waitcnt lgkmcnt(0)
	v_lshl_add_u64 v[22:23], s[30:31], 0, v[22:23]
	v_lshl_add_u64 v[22:23], s[6:7], 2, v[22:23]
	v_lshl_add_u64 v[22:23], v[22:23], 0, v[2:3]
	v_add_co_u32_e32 v24, vcc, s11, v22
	s_ashr_i32 s5, s4, 31
	s_nop 0
	v_addc_co_u32_e32 v25, vcc, 0, v23, vcc
	v_add_co_u32_e32 v26, vcc, s12, v22
	v_or_b32_e32 v28, s6, v29
	s_nop 0
	v_addc_co_u32_e32 v27, vcc, 0, v23, vcc
	v_add_co_u32_e32 v86, vcc, s13, v22
	v_or_b32_e32 v88, s6, v8
	s_nop 0
	v_addc_co_u32_e32 v87, vcc, 0, v23, vcc
	v_add_co_u32_e32 v94, vcc, s14, v22
	s_add_i32 s29, s29, s8
	s_nop 0
	v_addc_co_u32_e32 v95, vcc, 0, v23, vcc
	v_add_co_u32_e32 v96, vcc, s15, v22
	s_add_i32 s28, s28, s10
	s_nop 0
	v_addc_co_u32_e32 v97, vcc, 0, v23, vcc
	v_add_co_u32_e32 v98, vcc, s16, v22
	s_cmpk_gt_i32 s29, 0x2aff
	s_nop 0
	v_addc_co_u32_e32 v99, vcc, 0, v23, vcc
	v_add_co_u32_e32 v100, vcc, s17, v22
	s_nop 1
	v_addc_co_u32_e32 v101, vcc, 0, v23, vcc
	v_add_co_u32_e32 v102, vcc, s18, v22
	s_nop 1
	v_addc_co_u32_e32 v103, vcc, 0, v23, vcc
	v_add_co_u32_e32 v104, vcc, s19, v22
	s_nop 1
	v_addc_co_u32_e32 v105, vcc, 0, v23, vcc
	v_add_co_u32_e32 v106, vcc, s20, v22
	s_nop 1
	v_addc_co_u32_e32 v107, vcc, 0, v23, vcc
	v_add_co_u32_e32 v108, vcc, s21, v22
	s_nop 1
	v_addc_co_u32_e32 v109, vcc, 0, v23, vcc
	v_add_co_u32_e32 v110, vcc, s22, v22
	s_nop 1
	v_addc_co_u32_e32 v111, vcc, 0, v23, vcc
	v_add_co_u32_e32 v112, vcc, s23, v22
	s_nop 1
	v_addc_co_u32_e32 v113, vcc, 0, v23, vcc
	v_add_co_u32_e32 v114, vcc, s24, v22
	s_nop 1
	v_addc_co_u32_e32 v115, vcc, 0, v23, vcc
	v_add_co_u32_e32 v116, vcc, s25, v22
	s_nop 1
	v_addc_co_u32_e32 v117, vcc, 0, v23, vcc
	v_add_co_u32_e32 v118, vcc, s26, v22
	s_nop 1
	v_addc_co_u32_e32 v119, vcc, 0, v23, vcc
	global_load_dwordx4 v[22:25], v[24:25], off nt
	s_nop 0
	global_load_dwordx4 v[30:33], v[26:27], off nt
	global_load_dwordx4 v[34:37], v[86:87], off nt
	global_load_dwordx4 v[38:41], v[94:95], off nt
	global_load_dwordx4 v[42:45], v[96:97], off nt
	global_load_dwordx4 v[46:49], v[98:99], off nt
	global_load_dwordx4 v[50:53], v[100:101], off nt
	global_load_dwordx4 v[54:57], v[102:103], off nt
	global_load_dwordx4 v[58:61], v[104:105], off nt
	global_load_dwordx4 v[62:65], v[106:107], off nt
	global_load_dwordx4 v[66:69], v[108:109], off nt
	global_load_dwordx4 v[70:73], v[110:111], off nt
	global_load_dwordx4 v[74:77], v[112:113], off nt
	global_load_dwordx4 v[78:81], v[114:115], off nt
	global_load_dwordx4 v[82:85], v[116:117], off nt
	global_load_dwordx4 v[90:93], v[118:119], off nt
	v_or_b32_e32 v94, s6, v9
	v_or_b32_e32 v95, s6, v10
	v_or_b32_e32 v96, s6, v11
	v_or_b32_e32 v97, s6, v12
	v_lshl_add_u64 v[26:27], s[4:5], 1, v[6:7]
	v_or_b32_e32 v98, s6, v13
	v_or_b32_e32 v99, s6, v14
	v_mad_i64_i32 v[112:113], s[4:5], v94, s27, v[26:27]
	v_mad_i64_i32 v[114:115], s[4:5], v95, s27, v[26:27]
	v_mad_i64_i32 v[116:117], s[4:5], v96, s27, v[26:27]
	v_mad_i64_i32 v[118:119], s[4:5], v97, s27, v[26:27]
	v_mad_i64_i32 v[86:87], s[4:5], v28, s27, v[26:27]
	v_mad_i64_i32 v[110:111], s[4:5], v88, s27, v[26:27]
	v_mad_i64_i32 v[120:121], s[4:5], v98, s27, v[26:27]
	v_mad_i64_i32 v[26:27], s[4:5], v99, s27, v[26:27]
	s_waitcnt vmcnt(14)
	v_cvt_pk_bf16_f32 v94, v22, v30
	v_cvt_pk_bf16_f32 v22, v23, v31
	s_waitcnt vmcnt(12)
	v_cvt_pk_bf16_f32 v95, v34, v38
	v_cvt_pk_bf16_f32 v23, v35, v39
	s_waitcnt vmcnt(10)
	v_cvt_pk_bf16_f32 v96, v42, v46
	v_cvt_pk_bf16_f32 v30, v43, v47
	s_waitcnt vmcnt(8)
	v_cvt_pk_bf16_f32 v97, v50, v54
	v_cvt_pk_bf16_f32 v31, v51, v55
	s_waitcnt vmcnt(6)
	v_cvt_pk_bf16_f32 v98, v58, v62
	v_cvt_pk_bf16_f32 v34, v59, v63
	s_waitcnt vmcnt(4)
	v_cvt_pk_bf16_f32 v99, v66, v70
	v_cvt_pk_bf16_f32 v35, v67, v71
	s_waitcnt vmcnt(2)
	v_cvt_pk_bf16_f32 v100, v74, v78
	v_cvt_pk_bf16_f32 v38, v75, v79
	s_waitcnt vmcnt(0)
	v_cvt_pk_bf16_f32 v101, v82, v90
	v_cvt_pk_bf16_f32 v39, v83, v91
	v_cvt_pk_bf16_f32 v102, v24, v32
	v_cvt_pk_bf16_f32 v103, v36, v40
	v_cvt_pk_bf16_f32 v104, v44, v48
	v_cvt_pk_bf16_f32 v105, v52, v56
	v_cvt_pk_bf16_f32 v106, v60, v64
	v_cvt_pk_bf16_f32 v107, v68, v72
	v_cvt_pk_bf16_f32 v108, v76, v80
	v_cvt_pk_bf16_f32 v109, v84, v92
	v_cvt_pk_bf16_f32 v24, v25, v33
	v_cvt_pk_bf16_f32 v25, v37, v41
	v_cvt_pk_bf16_f32 v32, v45, v49
	v_cvt_pk_bf16_f32 v33, v53, v57
	v_cvt_pk_bf16_f32 v36, v61, v65
	v_cvt_pk_bf16_f32 v37, v69, v73
	v_cvt_pk_bf16_f32 v40, v77, v81
	v_cvt_pk_bf16_f32 v41, v85, v93
	ds_write_b128 v15, v[94:97]
	ds_write_b128 v15, v[98:101] offset:16
	ds_write2_b64 v15, v[22:23], v[30:31] offset0:17 offset1:18
	ds_write2_b64 v15, v[34:35], v[38:39] offset0:19 offset1:20
	ds_write_b128 v15, v[102:105] offset:272
	ds_write_b128 v15, v[106:109] offset:288
	ds_write2_b64 v15, v[24:25], v[32:33] offset0:51 offset1:52
	ds_write2_b64 v15, v[36:37], v[40:41] offset0:53 offset1:54
	s_waitcnt lgkmcnt(0)
	ds_read2_b64 v[22:25], v16 offset1:1
	ds_read2_b64 v[30:33], v16 offset0:136 offset1:137
	ds_read2_b64 v[34:37], v5 offset1:1
	ds_read2_b64 v[38:41], v17 offset1:1
	ds_read2_b64 v[42:45], v18 offset1:1
	ds_read2_b64 v[46:49], v19 offset1:1
	ds_read2_b64 v[50:53], v20 offset1:1
	ds_read2_b64 v[54:57], v21 offset1:1
	s_waitcnt lgkmcnt(7)
	global_store_dwordx4 v[86:87], v[22:25], off
	s_waitcnt lgkmcnt(6)
	global_store_dwordx4 v[110:111], v[30:33], off
	s_waitcnt lgkmcnt(5)
	global_store_dwordx4 v[112:113], v[34:37], off
	s_waitcnt lgkmcnt(4)
	global_store_dwordx4 v[114:115], v[38:41], off
	s_waitcnt lgkmcnt(3)
	global_store_dwordx4 v[116:117], v[42:45], off
	s_waitcnt lgkmcnt(2)
	global_store_dwordx4 v[118:119], v[46:49], off
	s_waitcnt lgkmcnt(1)
	global_store_dwordx4 v[120:121], v[50:53], off
	s_waitcnt lgkmcnt(0)
	global_store_dwordx4 v[26:27], v[54:57], off
	s_waitcnt lgkmcnt(0)
	s_cbranch_scc0 .LBB0_3563
	s_cmpk_ge_i32 s3, 0x440
	s_cbranch_scc1 .LBB0_3566
	v_mov_b32_e32 v3, 0
	v_lshlrev_b32_e32 v4, 1, v4
	v_mov_b32_e32 v5, v3
	v_lshl_add_u64 v[4:5], s[38:39], 0, v[4:5]
	s_mov_b64 s[4:5], 0x21600000
	v_lshl_add_u64 v[4:5], v[4:5], 0, s[4:5]
	s_mul_i32 s4, s3, 0xac000
	v_bfe_u32 v6, v0, 4, 2
	s_mov_b32 s5, 0x2b000
	v_mov_b32_e32 v7, s4
	v_mad_u32_u24 v6, v6, s5, v7
	s_mul_i32 s6, s8, 0xac000
	s_mov_b32 s7, 0xac00000
	s_mov_b32 s11, 0xac0a000
	s_mov_b32 s12, 0xac15000
	s_mov_b32 s13, 0xac20000
	s_mov_b32 s14, 0xac2b000
	s_mov_b32 s15, 0xac35000
	s_mov_b32 s16, 0xac40000
	s_mov_b32 s17, 0xac4b000
	s_mov_b32 s18, 0xac56000
	s_mov_b32 s19, 0xac60000
	s_mov_b32 s20, 0xac6b000
	s_mov_b32 s21, 0xac76000
	s_mov_b32 s22, 0xac81000
	s_mov_b32 s23, 0xac8b000
	s_mov_b32 s24, 0xac96000
	s_mov_b32 s25, 0xaca1000
.LBB0_3565:
	s_ashr_i32 s26, s3, 31
	s_mov_b64 s[4:5], s[0:1]
	s_lshr_b32 s26, s26, 26
	s_add_i32 s27, s3, s26
	s_load_dwordx2 s[4:5], s[4:5], 0xf8
	s_ashr_i32 s28, s27, 6
	s_mul_i32 s33, s28, 0xfd500000
	v_add_u32_e32 v18, s33, v6
	s_and_b32 s26, s27, 0xffffffc0
	v_ashrrev_i32_e32 v19, 31, v18
	s_and_b32 s29, s27, 64
	s_ashr_i32 s27, s26, 31
	s_waitcnt lgkmcnt(0)
	v_lshl_add_u64 v[18:19], v[18:19], 2, s[4:5]
	v_lshl_add_u64 v[18:19], s[26:27], 2, v[18:19]
	v_lshl_add_u64 v[18:19], v[18:19], 0, v[2:3]
	v_add_co_u32_e32 v20, vcc, s7, v18
	s_lshl_b32 s30, s28, 12
	s_nop 0
	v_addc_co_u32_e32 v21, vcc, 0, v19, vcc
	v_add_co_u32_e32 v88, vcc, s11, v18
	s_lshl_b32 s31, s28, 7
	s_nop 0
	v_addc_co_u32_e32 v89, vcc, 0, v19, vcc
	v_add_co_u32_e32 v90, vcc, s12, v18
	s_sub_i32 s28, s9, s30
	s_nop 0
	v_addc_co_u32_e32 v91, vcc, 0, v19, vcc
	v_add_co_u32_e32 v92, vcc, s13, v18
	s_and_b32 s30, s31, 0xffffff00
	s_nop 0
	v_addc_co_u32_e32 v93, vcc, 0, v19, vcc
	v_add_co_u32_e32 v94, vcc, s14, v18
	s_or_b32 s30, s30, s29
	s_nop 0
	v_addc_co_u32_e32 v95, vcc, 0, v19, vcc
	v_add_co_u32_e32 v96, vcc, s15, v18
	v_or_b32_e32 v86, s30, v29
	s_nop 0
	v_addc_co_u32_e32 v97, vcc, 0, v19, vcc
	v_add_co_u32_e32 v98, vcc, s16, v18
	s_ashr_i32 s29, s28, 31
	s_nop 0
	v_addc_co_u32_e32 v99, vcc, 0, v19, vcc
	v_add_co_u32_e32 v100, vcc, s17, v18
	v_ashrrev_i32_e32 v87, 31, v86
	s_nop 0
	v_addc_co_u32_e32 v101, vcc, 0, v19, vcc
	v_add_co_u32_e32 v102, vcc, s18, v18
	v_lshl_add_u64 v[26:27], s[28:29], 1, v[4:5]
	s_nop 0
	v_addc_co_u32_e32 v103, vcc, 0, v19, vcc
	v_add_co_u32_e32 v104, vcc, s19, v18
	v_lshlrev_b64 v[86:87], 13, v[86:87]
	s_nop 0
	v_addc_co_u32_e32 v105, vcc, 0, v19, vcc
	v_add_co_u32_e32 v106, vcc, s20, v18
	v_add_u32_e32 v7, 0x880, v16
	s_nop 0
	v_addc_co_u32_e32 v107, vcc, 0, v19, vcc
	v_add_co_u32_e32 v108, vcc, s21, v18
	v_add_u32_e32 v17, 0xcc0, v16
	s_nop 0
	v_addc_co_u32_e32 v109, vcc, 0, v19, vcc
	v_add_co_u32_e32 v110, vcc, s22, v18
	v_add_u32_e32 v28, 0x1100, v16
	s_nop 0
	v_addc_co_u32_e32 v111, vcc, 0, v19, vcc
	v_add_co_u32_e32 v112, vcc, s23, v18
	v_add_u32_e32 v118, 0x1540, v16
	s_nop 0
	v_addc_co_u32_e32 v113, vcc, 0, v19, vcc
	v_add_co_u32_e32 v114, vcc, s24, v18
	v_add_u32_e32 v119, 0x1980, v16
	s_nop 0
	v_addc_co_u32_e32 v115, vcc, 0, v19, vcc
	v_add_co_u32_e32 v116, vcc, s25, v18
	v_add_u32_e32 v120, 0x1dc0, v16
	s_nop 0
	v_addc_co_u32_e32 v117, vcc, 0, v19, vcc
	global_load_dwordx4 v[18:21], v[20:21], off nt
	s_nop 0
	global_load_dwordx4 v[22:25], v[88:89], off offset:3072 nt
	global_load_dwordx4 v[30:33], v[90:91], off offset:2048 nt
	global_load_dwordx4 v[34:37], v[92:93], off offset:1024 nt
	global_load_dwordx4 v[38:41], v[94:95], off nt
	global_load_dwordx4 v[42:45], v[96:97], off offset:3072 nt
	global_load_dwordx4 v[46:49], v[98:99], off offset:2048 nt
	global_load_dwordx4 v[50:53], v[100:101], off offset:1024 nt
	global_load_dwordx4 v[54:57], v[102:103], off nt
	global_load_dwordx4 v[58:61], v[104:105], off offset:3072 nt
	global_load_dwordx4 v[62:65], v[106:107], off offset:2048 nt
	global_load_dwordx4 v[66:69], v[108:109], off offset:1024 nt
	global_load_dwordx4 v[70:73], v[110:111], off nt
	global_load_dwordx4 v[74:77], v[112:113], off offset:3072 nt
	global_load_dwordx4 v[78:81], v[114:115], off offset:2048 nt
	global_load_dwordx4 v[82:85], v[116:117], off offset:1024 nt
	v_or_b32_e32 v88, s30, v8
	v_or_b32_e32 v90, s30, v9
	v_or_b32_e32 v92, s30, v10
	v_or_b32_e32 v94, s30, v11
	v_or_b32_e32 v96, s30, v12
	v_or_b32_e32 v98, s30, v13
	v_or_b32_e32 v100, s30, v14
	v_ashrrev_i32_e32 v89, 31, v88
	v_ashrrev_i32_e32 v91, 31, v90
	v_ashrrev_i32_e32 v93, 31, v92
	v_ashrrev_i32_e32 v95, 31, v94
	v_ashrrev_i32_e32 v97, 31, v96
	v_ashrrev_i32_e32 v99, 31, v98
	v_ashrrev_i32_e32 v101, 31, v100
	v_lshlrev_b64 v[88:89], 13, v[88:89]
	v_lshlrev_b64 v[90:91], 13, v[90:91]
	v_lshlrev_b64 v[92:93], 13, v[92:93]
	v_lshlrev_b64 v[94:95], 13, v[94:95]
	v_lshlrev_b64 v[96:97], 13, v[96:97]
	v_lshlrev_b64 v[98:99], 13, v[98:99]
	v_lshlrev_b64 v[100:101], 13, v[100:101]
	v_lshl_add_u64 v[102:103], v[26:27], 0, v[86:87]
	v_lshl_add_u64 v[104:105], v[26:27], 0, v[88:89]
	v_lshl_add_u64 v[106:107], v[26:27], 0, v[90:91]
	v_lshl_add_u64 v[108:109], v[26:27], 0, v[92:93]
	v_lshl_add_u64 v[110:111], v[26:27], 0, v[94:95]
	v_lshl_add_u64 v[112:113], v[26:27], 0, v[96:97]
	v_lshl_add_u64 v[114:115], v[26:27], 0, v[98:99]
	v_lshl_add_u64 v[26:27], v[26:27], 0, v[100:101]
	s_add_i32 s3, s3, s8
	s_add_i32 s9, s9, s10
	s_cmpk_lt_i32 s3, 0x440
	v_add_u32_e32 v6, s6, v6
	s_waitcnt vmcnt(14)
	v_cvt_pk_bf16_f32 v86, v18, v22
	v_cvt_pk_bf16_f32 v18, v19, v23
	s_waitcnt vmcnt(12)
	v_cvt_pk_bf16_f32 v87, v30, v34
	v_cvt_pk_bf16_f32 v19, v31, v35
	s_waitcnt vmcnt(10)
	v_cvt_pk_bf16_f32 v88, v38, v42
	v_cvt_pk_bf16_f32 v22, v39, v43
	s_waitcnt vmcnt(8)
	v_cvt_pk_bf16_f32 v89, v46, v50
	v_cvt_pk_bf16_f32 v23, v47, v51
	s_waitcnt vmcnt(6)
	v_cvt_pk_bf16_f32 v90, v54, v58
	v_cvt_pk_bf16_f32 v30, v55, v59
	s_waitcnt vmcnt(4)
	v_cvt_pk_bf16_f32 v91, v62, v66
	v_cvt_pk_bf16_f32 v31, v63, v67
	s_waitcnt vmcnt(2)
	v_cvt_pk_bf16_f32 v92, v70, v74
	v_cvt_pk_bf16_f32 v34, v71, v75
	s_waitcnt vmcnt(0)
	v_cvt_pk_bf16_f32 v93, v78, v82
	v_cvt_pk_bf16_f32 v35, v79, v83
	v_cvt_pk_bf16_f32 v94, v20, v24
	v_cvt_pk_bf16_f32 v95, v32, v36
	v_cvt_pk_bf16_f32 v96, v40, v44
	v_cvt_pk_bf16_f32 v97, v48, v52
	v_cvt_pk_bf16_f32 v98, v56, v60
	v_cvt_pk_bf16_f32 v99, v64, v68
	v_cvt_pk_bf16_f32 v100, v72, v76
	v_cvt_pk_bf16_f32 v101, v80, v84
	v_cvt_pk_bf16_f32 v20, v21, v25
	v_cvt_pk_bf16_f32 v21, v33, v37
	v_cvt_pk_bf16_f32 v24, v41, v45
	v_cvt_pk_bf16_f32 v25, v49, v53
	v_cvt_pk_bf16_f32 v32, v57, v61
	v_cvt_pk_bf16_f32 v33, v65, v69
	v_cvt_pk_bf16_f32 v36, v73, v77
	v_cvt_pk_bf16_f32 v37, v81, v85
	ds_write_b128 v15, v[86:89]
	ds_write_b128 v15, v[90:93] offset:16
	ds_write2_b64 v15, v[18:19], v[22:23] offset0:17 offset1:18
	ds_write2_b64 v15, v[30:31], v[34:35] offset0:19 offset1:20
	ds_write_b128 v15, v[94:97] offset:272
	ds_write_b128 v15, v[98:101] offset:288
	ds_write2_b64 v15, v[20:21], v[24:25] offset0:51 offset1:52
	ds_write2_b64 v15, v[32:33], v[36:37] offset0:53 offset1:54
	s_waitcnt lgkmcnt(0)
	ds_read2_b64 v[18:21], v16 offset1:1
	ds_read2_b64 v[22:25], v16 offset0:136 offset1:137
	ds_read2_b64 v[30:33], v7 offset1:1
	ds_read2_b64 v[34:37], v17 offset1:1
	ds_read2_b64 v[38:41], v28 offset1:1
	ds_read2_b64 v[42:45], v118 offset1:1
	ds_read2_b64 v[46:49], v119 offset1:1
	ds_read2_b64 v[50:53], v120 offset1:1
	s_waitcnt lgkmcnt(7)
	global_store_dwordx4 v[102:103], v[18:21], off
	s_waitcnt lgkmcnt(6)
	global_store_dwordx4 v[104:105], v[22:25], off
	s_waitcnt lgkmcnt(5)
	global_store_dwordx4 v[106:107], v[30:33], off
	s_waitcnt lgkmcnt(4)
	global_store_dwordx4 v[108:109], v[34:37], off
	s_waitcnt lgkmcnt(3)
	global_store_dwordx4 v[110:111], v[38:41], off
	s_waitcnt lgkmcnt(2)
	global_store_dwordx4 v[112:113], v[42:45], off
	s_waitcnt lgkmcnt(1)
	global_store_dwordx4 v[114:115], v[46:49], off
	s_waitcnt lgkmcnt(0)
	global_store_dwordx4 v[26:27], v[50:53], off
	s_waitcnt lgkmcnt(0)
	s_cbranch_scc1 .LBB0_3565
